# NSA cmp1/cmp2 loops: burst K/V/q global loads into 40 free VGPRs, counted vmcnt, K tile hoisted out of head loop
# speedup vs baseline: 1.1414x; 1.1414x over previous
; #define NEG_INF (-__builtin_inff())
; DI f32x16 mfma32(bf16x8 a, bf16x8 b, f32x16 c) { return __builtin_amdgcn_mfma_f32_32x32x16_bf16(a, b, c, 0, 0, 0); }
; DI f32x16 zero16() { f32x16 z; for (int i = 0; i < 16; ++i) z[i] = 0.f; return z; }
; DI int crow(int i, int g) { return (i & 3) + 8 * (i >> 2) + 4 * g; }
; DI f32x16 score_tile(const bf16x8 (&qf)[8], const bf16_t* __restrict__ Kp  , unsigned koff  ) {
;   f32x16 acc = zero16();
;   const char* kr = (const char*)Kp;
; #pragma unroll
;   for (int ks = 0; ks < 8; ++ks) { const bf16x8 a = *(const bf16x8*)(kr + (size_t)(koff + ks * 32)); acc = mfma32(a, qf[ks], acc); }
;   return acc;
; }
; DI void nsa_cmp1(const Params& p, const NsaCtx c) {
;     ...
;   for (int kt = 0; kt < ntile_c; ++kt) {
;     if (t0 - (16 * (32 * kt + 31) + 16) > thr + 32) continue;
;     f32x16 acc = score_tile(qf, KCMP + (size_t)kt * 32 * 128, koff);
;     float sc[16];
; #pragma unroll
;     for (int i = 0; i < 16; ++i) {
;       const int n = kt * 32 + crow(i, g);
;       const float s = acc[i] - slope2 * (ftq - ((float)(16 * n) + 15.5f));
;       sc[i] = (16 * n + 31 <= tq) ? s : NEG_INF;
;     }
.LBB0_209:
	v_cmp_gt_i32_e32 vcc, s3, v126
	s_cbranch_vccnz .LBB0_208
	s_mov_b64 s[6:7], s[8:9]
	v_lshl_add_u64 v[66:67], v[120:121], 0, s[6:7]
	v_add_co_u32_e32 v134, vcc, 0x2a4e5000, v66
	v_add_u32_e32 v129, 0xfffffe31, v0
	s_nop 0
	v_addc_co_u32_e32 v135, vcc, 0, v67, vcc
	global_load_dwordx4 v[186:189], v[134:135], off
	global_load_dwordx4 v[194:197], v[134:135], off offset:32
	global_load_dwordx4 v[200:203], v[134:135], off offset:64
	global_load_dwordx4 v[228:231], v[134:135], off offset:96
	global_load_dwordx4 v[232:235], v[134:135], off offset:128
	global_load_dwordx4 v[236:239], v[134:135], off offset:160
	global_load_dwordx4 v[240:243], v[134:135], off offset:192
	global_load_dwordx4 v[244:247], v[134:135], off offset:224
	v_cvt_f32_i32_e32 v129, v129
	s_mov_b32 s5, 0xff800000
	v_add_f32_e32 v129, 0x41780000, v129
	v_sub_f32_e32 v129, v125, v129
	v_lshl_add_u64 v[204:205], v[118:119], 0, s[6:7]
	v_lshl_add_u64 v[226:227], v[116:117], 0, s[6:7]
	v_add_co_u32_e32 v190, vcc, 0x2a565000, v204
	s_nop 1
	v_addc_co_u32_e32 v191, vcc, 0, v205, vcc
	v_add_co_u32_e32 v204, vcc, 0x2a566000, v204
	s_nop 1
	v_addc_co_u32_e32 v205, vcc, 0, v205, vcc
	v_add_co_u32_e32 v226, vcc, 0x2a566000, v226
	s_nop 1
	v_addc_co_u32_e32 v227, vcc, 0, v227, vcc
	s_waitcnt vmcnt(7)
	v_mfma_f32_32x32x16_bf16 v[66:81], v[186:189], v[110:113], 0
	s_waitcnt vmcnt(6)
	v_mfma_f32_32x32x16_bf16 v[66:81], v[194:197], v[106:109], v[66:81]
	s_waitcnt vmcnt(5)
	v_mfma_f32_32x32x16_bf16 v[66:81], v[200:203], v[102:105], v[66:81]
	s_waitcnt vmcnt(4)
	v_mfma_f32_32x32x16_bf16 v[66:81], v[228:231], v[98:101], v[66:81]
	s_waitcnt vmcnt(3)
	v_mfma_f32_32x32x16_bf16 v[66:81], v[232:235], v[94:97], v[66:81]
	s_waitcnt vmcnt(2)
	v_mfma_f32_32x32x16_bf16 v[66:81], v[236:239], v[90:93], v[66:81]
	s_waitcnt vmcnt(1)
	v_mfma_f32_32x32x16_bf16 v[66:81], v[240:243], v[86:89], v[66:81]
	s_waitcnt vmcnt(0)
	v_mfma_f32_32x32x16_bf16 v[66:81], v[244:247], v[82:85], v[66:81]
	global_load_dwordx2 v[186:187], v[190:191], off
	global_load_dwordx2 v[188:189], v[190:191], off offset:16
	global_load_dwordx2 v[194:195], v[190:191], off offset:32
	global_load_dwordx2 v[196:197], v[190:191], off offset:48
	global_load_dwordx2 v[200:201], v[190:191], off offset:2048
	global_load_dwordx2 v[202:203], v[190:191], off offset:2064
	global_load_dwordx2 v[228:229], v[190:191], off offset:2080
	global_load_dwordx2 v[230:231], v[190:191], off offset:2096
	global_load_dwordx2 v[232:233], v[204:205], off
	global_load_dwordx2 v[234:235], v[204:205], off offset:16
	global_load_dwordx2 v[236:237], v[226:227], off
	global_load_dwordx2 v[238:239], v[226:227], off offset:16
	global_load_dwordx2 v[240:241], v[204:205], off offset:2048
	global_load_dwordx2 v[242:243], v[204:205], off offset:2064
	global_load_dwordx2 v[244:245], v[226:227], off offset:2048
	global_load_dwordx2 v[246:247], v[226:227], off offset:2064
	v_fma_f32 v66, -v124, v129, v66
	v_add_u32_e32 v129, 0xfffffe50, v0
	v_cmp_le_i32_e32 vcc, v129, v114
	v_add_u32_e32 v129, 0xfffffe41, v0
	v_cvt_f32_i32_e32 v129, v129
	v_cndmask_b32_e32 v66, v248, v66, vcc
	v_add_f32_e32 v129, 0x41780000, v129
	v_sub_f32_e32 v129, v125, v129
	v_fma_f32 v67, -v124, v129, v67
	v_add_u32_e32 v129, 0xfffffe60, v0
	v_cmp_le_i32_e32 vcc, v129, v114
	v_add_u32_e32 v129, 0xfffffe51, v0
	v_cvt_f32_i32_e32 v129, v129
	v_cndmask_b32_e32 v67, v248, v67, vcc
	v_add_f32_e32 v129, 0x41780000, v129
	v_sub_f32_e32 v129, v125, v129
	v_fma_f32 v68, -v124, v129, v68
	v_add_u32_e32 v129, 0xfffffe70, v0
	v_cmp_le_i32_e32 vcc, v129, v114
	v_add_u32_e32 v129, 0xfffffe61, v0
	v_cvt_f32_i32_e32 v129, v129
	v_cndmask_b32_e32 v68, v248, v68, vcc
	v_add_f32_e32 v129, 0x41780000, v129
	v_sub_f32_e32 v129, v125, v129
	v_fma_f32 v69, -v124, v129, v69
	v_add_u32_e32 v129, 0xfffffe80, v0
	v_cmp_le_i32_e32 vcc, v129, v114
	v_add_u32_e32 v129, 0xfffffeb1, v0
	v_cvt_f32_i32_e32 v129, v129
	v_cndmask_b32_e32 v69, v248, v69, vcc
	v_add_f32_e32 v129, 0x41780000, v129
	v_sub_f32_e32 v129, v125, v129
	v_fma_f32 v70, -v124, v129, v70
	v_add_u32_e32 v129, 0xfffffed0, v0
	v_cmp_le_i32_e32 vcc, v129, v114
	v_add_u32_e32 v129, 0xfffffec1, v0
	v_cvt_f32_i32_e32 v129, v129
	v_cndmask_b32_e32 v70, v248, v70, vcc
	v_add_f32_e32 v129, 0x41780000, v129
	v_sub_f32_e32 v129, v125, v129
	v_fma_f32 v71, -v124, v129, v71
	v_add_u32_e32 v129, 0xfffffee0, v0
	v_cmp_le_i32_e32 vcc, v129, v114
	v_add_u32_e32 v129, 0xfffffed1, v0
	v_cvt_f32_i32_e32 v129, v129
	v_cndmask_b32_e32 v71, v248, v71, vcc
	v_add_f32_e32 v129, 0x41780000, v129
	v_sub_f32_e32 v129, v125, v129
	v_fma_f32 v72, -v124, v129, v72
	v_add_u32_e32 v129, 0xfffffef0, v0
	v_cmp_le_i32_e32 vcc, v129, v114
	v_add_u32_e32 v129, 0xfffffee1, v0
	v_cvt_f32_i32_e32 v129, v129
	v_cndmask_b32_e32 v72, v248, v72, vcc
	v_add_f32_e32 v129, 0x41780000, v129
	v_sub_f32_e32 v129, v125, v129
	v_fma_f32 v73, -v124, v129, v73
	v_add_u32_e32 v129, 0xffffff00, v0
	v_cmp_le_i32_e32 vcc, v129, v114
	v_add_u32_e32 v129, 0xffffff31, v0
	v_cvt_f32_i32_e32 v129, v129
	v_cndmask_b32_e32 v73, v248, v73, vcc
	v_add_f32_e32 v129, 0x41780000, v129
	v_sub_f32_e32 v129, v125, v129
	v_fma_f32 v74, -v124, v129, v74
	v_add_u32_e32 v129, 0xffffff50, v0
	v_cmp_le_i32_e32 vcc, v129, v114
	v_add_u32_e32 v129, 0xffffff41, v0
	v_cvt_f32_i32_e32 v129, v129
	v_cndmask_b32_e32 v74, v248, v74, vcc
	v_add_f32_e32 v129, 0x41780000, v129
	v_sub_f32_e32 v129, v125, v129
	v_fma_f32 v75, -v124, v129, v75
	v_add_u32_e32 v129, 0xffffff60, v0
	v_cmp_le_i32_e32 vcc, v129, v114
	v_add_u32_e32 v129, 0xffffff51, v0
	v_cvt_f32_i32_e32 v129, v129
	v_cndmask_b32_e32 v75, v248, v75, vcc
	v_add_f32_e32 v129, 0x41780000, v129
; #define NEG_INF (-__builtin_inff())
; DI float xhalf_max(float v) { const auto r = __builtin_amdgcn_permlane32_swap(__float_as_uint(v), __float_as_uint(v), false, false); return fmaxf(__uint_as_float(r[0]), __uint_as_float(r[1])); }
; DI float fexp2(float x) { return __builtin_amdgcn_exp2f(x); }
; DI f32x16 mfma32(bf16x8 a, bf16x8 b, f32x16 c) { return __builtin_amdgcn_mfma_f32_32x32x16_bf16(a, b, c, 0, 0, 0); }
; DI bf16x8 pack8(const float* p) { u32x4 o; o.x = pk2h(p[0], p[1]); o.y = pk2h(p[2], p[3]); o.z = pk2h(p[4], p[5]); o.w = pk2h(p[6], p[7]); return __builtin_bit_cast(bf16x8, o); }
; DI void pv_tile(f32x16 (&o)[4], const bf16x8 (&pf)[2], const bf16_t* __restrict__ VTp  , size_t ldv, unsigned voff  ) {
; #pragma unroll
;   for (int vt = 0; vt < 4; ++vt) {
;     const char* vr = (const char*)(VTp + (size_t)(vt * 32) * ldv);
; #pragma unroll
;     for (int s = 0; s < 2; ++s) {
;       const s16x4 lo = *(const s16x4*)(vr + (size_t)(voff + 32 * s)), hi = *(const s16x4*)(vr + (size_t)(voff + 32 * s + 16));
;       const bf16x8 a = __builtin_shufflevector(lo, hi, 0, 1, 2, 3, 4, 5, 6, 7);
;       o[vt] = mfma32(a, pf[s], o[vt]);
;     }
;   }
; }
; DI void softmax_step(AttnState& st, float (&sc)[16], const bf16_t* __restrict__ VTp, size_t ldv, unsigned voff) {
;   float mx = st.m;
; #pragma unroll
;   for (int i = 0; i < 16; ++i) mx = fmaxf(mx, sc[i]);
;   mx = xhalf_max(mx);
;   const float ms = (mx == NEG_INF) ? 0.f : mx;
;   const float alpha = fexp2(st.m - ms);
;   st.m = mx;
;   float ps = 0.f;
; #pragma unroll
;   for (int i = 0; i < 16; ++i) { sc[i] = fexp2(sc[i] - ms); ps += sc[i]; }
;   st.l = st.l * alpha + ps;
; #pragma unroll
;   for (int vt = 0; vt < 4; ++vt)
; #pragma unroll
;     for (int i = 0; i < 16; ++i) st.o[vt][i] *= alpha;
;   bf16x8 pf[2]; pf[0] = pack8(sc); pf[1] = pack8(sc + 8);
;   pv_tile(st.o, pf, VTp, ldv, voff);
; }
	v_sub_f32_e32 v129, v125, v129
	v_fma_f32 v76, -v124, v129, v76
	v_add_u32_e32 v129, 0xffffff70, v0
	v_cmp_le_i32_e32 vcc, v129, v114
	v_add_u32_e32 v129, 0xffffff61, v0
	v_cvt_f32_i32_e32 v129, v129
	v_cndmask_b32_e32 v76, v248, v76, vcc
	v_add_f32_e32 v129, 0x41780000, v129
	v_sub_f32_e32 v129, v125, v129
	v_fma_f32 v77, -v124, v129, v77
	v_add_u32_e32 v129, 0xffffff80, v0
	v_cmp_le_i32_e32 vcc, v129, v114
	v_add_u32_e32 v129, 0xffffffb1, v0
	v_cvt_f32_i32_e32 v129, v129
	v_cndmask_b32_e32 v77, v248, v77, vcc
	v_add_f32_e32 v129, 0x41780000, v129
	v_sub_f32_e32 v129, v125, v129
	v_fma_f32 v78, -v124, v129, v78
	v_subrev_u32_e32 v129, 48, v0
	v_cmp_le_i32_e32 vcc, v129, v114
	s_nop 1
	v_cndmask_b32_e32 v129, v248, v78, vcc
	v_subrev_u32_e32 v78, 63, v0
	v_cvt_f32_i32_e32 v78, v78
	v_add_f32_e32 v78, 0x41780000, v78
	v_sub_f32_e32 v78, v125, v78
	v_fma_f32 v78, -v124, v78, v79
	v_subrev_u32_e32 v79, 32, v0
	v_cmp_le_i32_e32 vcc, v79, v114
	s_nop 1
	v_cndmask_b32_e32 v79, v248, v78, vcc
	v_subrev_u32_e32 v78, 47, v0
	v_cvt_f32_i32_e32 v78, v78
	v_add_f32_e32 v78, 0x41780000, v78
	v_sub_f32_e32 v78, v125, v78
	v_fma_f32 v78, -v124, v78, v80
	v_add_u32_e32 v80, -16, v0
	v_cmp_le_i32_e32 vcc, v80, v114
	s_nop 1
	v_cndmask_b32_e32 v80, v248, v78, vcc
	v_subrev_u32_e32 v78, 31, v0
	v_cvt_f32_i32_e32 v78, v78
	v_cmp_le_i32_e32 vcc, v0, v114
	v_add_f32_e32 v78, 0x41780000, v78
	v_sub_f32_e32 v78, v125, v78
	v_fma_f32 v78, -v124, v78, v81
	v_cndmask_b32_e32 v81, v248, v78, vcc
	v_max3_f32 v78, v127, v66, v67
	v_max3_f32 v78, v78, v68, v69
	v_max3_f32 v78, v78, v70, v71
	v_max3_f32 v78, v78, v72, v73
	v_max3_f32 v78, v78, v74, v75
	v_max3_f32 v78, v78, v76, v77
	v_max3_f32 v78, v78, v129, v79
	v_max3_f32 v78, v78, v80, v81
	v_mov_b32_e32 v130, v78
	s_nop 1
	v_permlane32_swap_b32_e32 v78, v130
	v_max_f32_e32 v130, v130, v130
	v_max_f32_e32 v78, v78, v78
	v_max_f32_e32 v78, v78, v130
	v_cmp_neq_f32_e32 vcc, s5, v78
	s_mov_b32 s5, 0x2a565000
	s_nop 0
	v_cndmask_b32_e32 v130, 0, v78, vcc
	v_sub_f32_e32 v66, v66, v130
	v_exp_f32_e32 v131, v66
	v_sub_f32_e32 v67, v67, v130
	v_exp_f32_e32 v67, v67
	v_sub_f32_e32 v68, v68, v130
	v_exp_f32_e32 v68, v68
	v_sub_f32_e32 v69, v69, v130
	v_exp_f32_e32 v69, v69
	v_sub_f32_e32 v70, v70, v130
	v_add_f32_e32 v66, 0, v131
	v_exp_f32_e32 v132, v70
	v_sub_f32_e32 v70, v71, v130
	v_add_f32_e32 v66, v67, v66
	v_exp_f32_e32 v133, v70
	v_sub_f32_e32 v70, v72, v130
	v_add_f32_e32 v66, v68, v66
	v_exp_f32_e32 v134, v70
	v_sub_f32_e32 v70, v73, v130
	v_add_f32_e32 v66, v69, v66
	v_exp_f32_e32 v73, v70
	v_sub_f32_e32 v70, v74, v130
	v_add_f32_e32 v66, v132, v66
	v_exp_f32_e32 v74, v70
	v_sub_f32_e32 v70, v75, v130
	v_add_f32_e32 v66, v133, v66
	v_exp_f32_e32 v75, v70
	v_sub_f32_e32 v70, v76, v130
	v_add_f32_e32 v66, v134, v66
	v_exp_f32_e32 v76, v70
	v_sub_f32_e32 v70, v77, v130
	v_add_f32_e32 v66, v73, v66
	v_exp_f32_e32 v77, v70
	v_sub_f32_e32 v70, v129, v130
	v_add_f32_e32 v66, v74, v66
	v_exp_f32_e32 v129, v70
	v_sub_f32_e32 v70, v79, v130
	v_add_f32_e32 v66, v75, v66
	v_exp_f32_e32 v135, v70
	v_sub_f32_e32 v70, v80, v130
	v_add_f32_e32 v66, v76, v66
	v_exp_f32_e32 v80, v70
	v_sub_f32_e32 v70, v81, v130
	v_add_f32_e32 v66, v77, v66
	v_exp_f32_e32 v81, v70
	v_add_f32_e32 v66, v129, v66
	v_add_f32_e32 v66, v135, v66
	v_sub_f32_e32 v127, v127, v130
	v_add_f32_e32 v66, v80, v66
	v_add_f32_e32 v79, v81, v66
	v_exp_f32_e32 v66, v127
	v_cvt_pk_bf16_f32 v70, v131, v67
	v_cvt_pk_bf16_f32 v71, v68, v69
	v_cvt_pk_bf16_f32 v68, v129, v135
	v_fmac_f32_e32 v79, v128, v66
	v_pk_mul_f32 v[64:65], v[64:65], v[66:67] op_sel_hi:[1,0]
	v_pk_mul_f32 v[62:63], v[62:63], v[66:67] op_sel_hi:[1,0]
	v_pk_mul_f32 v[60:61], v[60:61], v[66:67] op_sel_hi:[1,0]
	v_pk_mul_f32 v[58:59], v[58:59], v[66:67] op_sel_hi:[1,0]
	v_pk_mul_f32 v[56:57], v[56:57], v[66:67] op_sel_hi:[1,0]
	v_pk_mul_f32 v[54:55], v[54:55], v[66:67] op_sel_hi:[1,0]
	v_pk_mul_f32 v[52:53], v[52:53], v[66:67] op_sel_hi:[1,0]
	v_pk_mul_f32 v[50:51], v[50:51], v[66:67] op_sel_hi:[1,0]
	v_pk_mul_f32 v[48:49], v[48:49], v[66:67] op_sel_hi:[1,0]
	v_pk_mul_f32 v[46:47], v[46:47], v[66:67] op_sel_hi:[1,0]
	v_pk_mul_f32 v[44:45], v[44:45], v[66:67] op_sel_hi:[1,0]
	v_pk_mul_f32 v[42:43], v[42:43], v[66:67] op_sel_hi:[1,0]
	v_pk_mul_f32 v[40:41], v[40:41], v[66:67] op_sel_hi:[1,0]
	v_pk_mul_f32 v[38:39], v[38:39], v[66:67] op_sel_hi:[1,0]
	v_pk_mul_f32 v[36:37], v[36:37], v[66:67] op_sel_hi:[1,0]
	v_pk_mul_f32 v[34:35], v[34:35], v[66:67] op_sel_hi:[1,0]
	v_pk_mul_f32 v[32:33], v[32:33], v[66:67] op_sel_hi:[1,0]
	v_pk_mul_f32 v[30:31], v[30:31], v[66:67] op_sel_hi:[1,0]
	v_pk_mul_f32 v[28:29], v[28:29], v[66:67] op_sel_hi:[1,0]
	v_pk_mul_f32 v[26:27], v[26:27], v[66:67] op_sel_hi:[1,0]
	v_pk_mul_f32 v[24:25], v[24:25], v[66:67] op_sel_hi:[1,0]
	v_pk_mul_f32 v[22:23], v[22:23], v[66:67] op_sel_hi:[1,0]
	v_pk_mul_f32 v[20:21], v[20:21], v[66:67] op_sel_hi:[1,0]
	v_pk_mul_f32 v[18:19], v[18:19], v[66:67] op_sel_hi:[1,0]
	v_pk_mul_f32 v[16:17], v[16:17], v[66:67] op_sel_hi:[1,0]
	v_pk_mul_f32 v[14:15], v[14:15], v[66:67] op_sel_hi:[1,0]
	v_pk_mul_f32 v[12:13], v[12:13], v[66:67] op_sel_hi:[1,0]
	v_pk_mul_f32 v[10:11], v[10:11], v[66:67] op_sel_hi:[1,0]
	v_pk_mul_f32 v[8:9], v[8:9], v[66:67] op_sel_hi:[1,0]
	v_pk_mul_f32 v[6:7], v[6:7], v[66:67] op_sel_hi:[1,0]
	v_pk_mul_f32 v[4:5], v[4:5], v[66:67] op_sel_hi:[1,0]
	v_pk_mul_f32 v[2:3], v[2:3], v[66:67] op_sel_hi:[1,0]
	v_cvt_pk_bf16_f32 v66, v74, v75
	v_cvt_pk_bf16_f32 v67, v76, v77
	v_cvt_pk_bf16_f32 v72, v132, v133
	v_cvt_pk_bf16_f32 v73, v134, v73
	v_cvt_pk_bf16_f32 v69, v80, v81
	v_mov_b32_e32 v127, v78
	v_mov_b32_e32 v128, v79
	s_waitcnt vmcnt(14)
	v_mfma_f32_32x32x16_bf16 v[50:65], v[186:189], v[70:73], v[50:65]
	s_waitcnt vmcnt(12)
	v_mfma_f32_32x32x16_bf16 v[50:65], v[194:197], v[66:69], v[50:65]
	s_waitcnt vmcnt(10)
	v_mfma_f32_32x32x16_bf16 v[34:49], v[200:203], v[70:73], v[34:49]
	s_waitcnt vmcnt(8)
	v_mfma_f32_32x32x16_bf16 v[34:49], v[228:231], v[66:69], v[34:49]
	s_waitcnt vmcnt(6)
	v_mfma_f32_32x32x16_bf16 v[18:33], v[232:235], v[70:73], v[18:33]
	s_waitcnt vmcnt(4)
	v_mfma_f32_32x32x16_bf16 v[18:33], v[236:239], v[66:69], v[18:33]
	s_waitcnt vmcnt(2)
	v_mfma_f32_32x32x16_bf16 v[2:17], v[240:243], v[70:73], v[2:17]
	s_waitcnt vmcnt(0)
	v_mfma_f32_32x32x16_bf16 v[2:17], v[244:247], v[66:69], v[2:17]
	s_branch .LBB0_208

; DI float fexp2(float x) { return __builtin_amdgcn_exp2f(x); }
; DI int crow(int i, int g) { return (i & 3) + 8 * (i >> 2) + 4 * g; }
; DI void nsa_cmp2(const Params& p, const NsaCtx c) {
;     ...
; #pragma unroll 1
;   for (int kk = 0; kk < 2; ++kk) {
;     const int kt = j + 4 * kk;
;     float ps[16];
; #pragma unroll
;     for (int i = 0; i < 16; ++i) ps[i] = 0.f;
;     if (kt < ntile_c) {
; #pragma unroll 1
;       for (int jj = 0; jj < 4; ++jj) {
;         const int hh = c.gk * 4 + jj;
;         bf16x8 q2[8];
;         load_q_norm(q2, NQ + ((size_t)(c.b * 16 + hh) * T_ + tq) * 128, g, qgain, ATTN_SCALE * LOG2E);
;         const float sl2 = fexp2(-0.5f * (float)(hh + 1)) * LOG2E;
;         if (t0 - (16 * (32 * kt + 31) + 16) > __builtin_amdgcn_readfirstlane((int)(200.f / sl2) + 1) + 32) continue;
;         const float mm = ml[((sub * 4 + jj) * 32 + lr) * 2], iv = ml[((sub * 4 + jj) * 32 + lr) * 2 + 1];
;         f32x16 acc = score_tile(q2, KCMP + (size_t)kt * 32 * 128, koff);
; #pragma unroll
;         for (int i = 0; i < 16; ++i) {
;           const int n = kt * 32 + crow(i, g);
;           const float s = acc[i] - sl2 * (ftq - ((float)(16 * n) + 15.5f));
;           const float pr = (16 * n + 31 <= tq) ? fexp2(s - mm) * iv : 0.f;
.LBB0_218:
	s_or_b32 s6, s6, s2
	v_mov_b32_e32 v96, 0
	s_cmp_gt_i32 s6, s3
	v_mov_b32_e32 v95, 0
	v_mov_b32_e32 v92, 0
	v_mov_b32_e32 v91, 0
	v_mov_b32_e32 v88, 0
	v_mov_b32_e32 v87, 0
	v_mov_b32_e32 v84, 0
	v_mov_b32_e32 v83, 0
	v_mov_b32_e32 v94, 0
	v_mov_b32_e32 v97, 0
	v_mov_b32_e32 v90, 0
	v_mov_b32_e32 v93, 0
	v_mov_b32_e32 v86, 0
	v_mov_b32_e32 v89, 0
	v_mov_b32_e32 v82, 0
	v_mov_b32_e32 v85, 0
	s_cbranch_scc1 .LBB0_217
	global_load_dwordx4 v[18:21], v[128:129], off offset:16
	global_load_dwordx4 v[22:25], v[128:129], off
	global_load_dwordx4 v[26:29], v[128:129], off offset:80
	global_load_dwordx4 v[30:33], v[128:129], off offset:64
	global_load_dwordx4 v[34:37], v[128:129], off offset:144
	global_load_dwordx4 v[38:41], v[128:129], off offset:128
	global_load_dwordx4 v[42:45], v[128:129], off offset:208
	global_load_dwordx4 v[46:49], v[128:129], off offset:192
	global_load_dwordx4 v[50:53], v[128:129], off offset:272
	global_load_dwordx4 v[54:57], v[128:129], off offset:256
	global_load_dwordx4 v[58:61], v[128:129], off offset:336
	global_load_dwordx4 v[62:65], v[128:129], off offset:320
	global_load_dwordx4 v[66:69], v[128:129], off offset:400
	global_load_dwordx4 v[70:73], v[128:129], off offset:384
	global_load_dwordx4 v[74:77], v[128:129], off offset:464
	global_load_dwordx4 v[78:81], v[128:129], off offset:448
	v_readlane_b32 s10, v253, 10
	v_readlane_b32 s11, v253, 11
	s_lshl_b32 s8, s6, 9
	s_mov_b32 s9, s11
	s_sub_i32 s7, s4, s8
	v_writelane_b32 v253, s8, 10
	s_lshl_b32 s10, s6, 13
	v_mov_b32_e32 v85, 0
	v_or_b32_e32 v0, s8, v172
	v_cvt_f32_u32_e32 v3, v0
	v_or_b32_e32 v4, 16, v0
	v_or_b32_e32 v2, 31, v0
	v_cvt_f32_u32_e32 v4, v4
	v_cmp_gt_i32_e64 s[38:39], v2, v126
	v_add_f32_e32 v2, 0x41780000, v3
	v_or_b32_e32 v3, 32, v0
	v_cvt_f32_u32_e32 v3, v3
	v_sub_f32_e32 v83, v170, v2
	v_add_f32_e32 v2, 0x41780000, v4
	v_sub_f32_e32 v84, v170, v2
	v_or_b32_e32 v2, 63, v0
	v_cmp_gt_i32_e64 s[40:41], v2, v127
	v_add_f32_e32 v2, 0x41780000, v3
	v_or_b32_e32 v3, 48, v0
	v_cvt_f32_u32_e32 v3, v3
	v_sub_f32_e32 v87, v170, v2
	v_add_u32_e32 v2, 0x4f, v0
	v_cmp_gt_i32_e64 s[44:45], v2, v126
	v_add_f32_e32 v2, 0x41780000, v3
	v_or_b32_e32 v3, 0x80, v0
	v_cvt_f32_u32_e32 v3, v3
	v_or_b32_e32 v4, 47, v0
	v_cmp_gt_i32_e64 s[42:43], v4, v126
	v_or_b32_e32 v4, 0x90, v0
	v_sub_f32_e32 v88, v170, v2
	v_or_b32_e32 v2, 0x9f, v0
	v_cvt_f32_u32_e32 v4, v4
	v_cmp_gt_i32_e64 s[46:47], v2, v126
	v_add_f32_e32 v2, 0x41780000, v3
	v_or_b32_e32 v3, 0xa0, v0
	v_cvt_f32_u32_e32 v3, v3
	v_sub_f32_e32 v91, v170, v2
	v_add_f32_e32 v2, 0x41780000, v4
	v_sub_f32_e32 v92, v170, v2
	v_or_b32_e32 v2, 0xbf, v0
	v_cmp_gt_i32_e64 s[48:49], v2, v127
	v_add_f32_e32 v2, 0x41780000, v3
	v_or_b32_e32 v3, 0xb0, v0
	v_cvt_f32_u32_e32 v3, v3
	v_sub_f32_e32 v95, v170, v2
	v_add_u32_e32 v2, 0xcf, v0
	v_cmp_gt_i32_e64 s[52:53], v2, v126
	v_add_f32_e32 v2, 0x41780000, v3
	v_or_b32_e32 v3, 0x100, v0
	v_cvt_f32_u32_e32 v3, v3
	v_or_b32_e32 v4, 0xaf, v0
	v_cmp_gt_i32_e64 s[50:51], v4, v126
	v_or_b32_e32 v4, 0x110, v0
	v_sub_f32_e32 v96, v170, v2
	v_or_b32_e32 v2, 0x11f, v0
	v_cvt_f32_u32_e32 v4, v4
	v_cmp_gt_i32_e64 s[54:55], v2, v126
	v_add_f32_e32 v2, 0x41780000, v3
	v_or_b32_e32 v3, 0x120, v0
	v_cvt_f32_u32_e32 v3, v3
	v_sub_f32_e32 v174, v170, v2
	v_add_f32_e32 v2, 0x41780000, v4
	v_sub_f32_e32 v175, v170, v2
	v_or_b32_e32 v2, 0x13f, v0
	v_cmp_gt_i32_e64 s[56:57], v2, v127
	v_add_f32_e32 v2, 0x41780000, v3
	v_or_b32_e32 v3, 0x130, v0
	v_cvt_f32_u32_e32 v3, v3
	v_sub_f32_e32 v180, v170, v2
	v_add_u32_e32 v2, 0x14f, v0
	v_cmp_gt_i32_e64 s[60:61], v2, v126
	v_add_f32_e32 v2, 0x41780000, v3
	v_or_b32_e32 v3, 0x180, v0
	v_cvt_f32_u32_e32 v3, v3
	v_or_b32_e32 v4, 0x12f, v0
	v_cmp_gt_i32_e64 s[58:59], v4, v126
	v_or_b32_e32 v4, 0x190, v0
	v_sub_f32_e32 v181, v170, v2
	v_or_b32_e32 v2, 0x19f, v0
	v_cvt_f32_u32_e32 v4, v4
	v_cmp_gt_i32_e64 s[62:63], v2, v126
	v_add_f32_e32 v2, 0x41780000, v3
	v_or_b32_e32 v3, 0x1a0, v0
	v_cvt_f32_u32_e32 v3, v3
	v_sub_f32_e32 v182, v170, v2
	v_add_f32_e32 v2, 0x41780000, v4
	v_sub_f32_e32 v183, v170, v2
	v_or_b32_e32 v2, 0x1bf, v0
	v_cmp_gt_i32_e64 s[64:65], v2, v127
	v_add_f32_e32 v2, 0x41780000, v3
	v_or_b32_e32 v3, 0x1b0, v0
	v_cvt_f32_u32_e32 v3, v3
	v_or_b32_e32 v4, 0x1af, v0
	v_add_u32_e32 v0, 0x1cf, v0
	v_cmp_gt_i32_e64 s[68:69], v0, v126
	v_add_f32_e32 v0, 0x41780000, v3
	v_sub_f32_e32 v185, v170, v0
	v_mov_b32_e32 v0, v1
	v_writelane_b32 v253, s9, 11
	v_lshl_add_u64 v[134:135], v[130:131], 0, s[10:11]
	global_load_dwordx4 v[186:189], v[134:135], off
	global_load_dwordx4 v[194:197], v[134:135], off offset:32
	global_load_dwordx4 v[200:203], v[134:135], off offset:64
	global_load_dwordx4 v[228:231], v[134:135], off offset:96
	global_load_dwordx4 v[232:235], v[134:135], off offset:128
	global_load_dwordx4 v[236:239], v[134:135], off offset:160
	global_load_dwordx4 v[240:243], v[134:135], off offset:192
	global_load_dwordx4 v[244:247], v[134:135], off offset:224
	v_cmp_gt_i32_e64 s[66:67], v4, v126
	v_sub_f32_e32 v184, v170, v2
	s_mov_b32 s8, 0
	v_mov_b64_e32 v[140:141], v[132:133]
	v_mov_b32_e32 v207, v173
	v_mov_b32_e32 v82, v85
	v_mov_b32_e32 v89, v85
	v_mov_b32_e32 v86, v85
	v_mov_b32_e32 v93, v85
	v_mov_b32_e32 v90, v85
	v_mov_b32_e32 v97, v85
	v_mov_b32_e32 v94, v85
	v_mov_b64_e32 v[136:137], v[0:1]
	v_mov_b64_e32 v[138:139], v[0:1]
	v_mov_b64_e32 v[142:143], v[0:1]
	v_mov_b64_e32 v[144:145], v[0:1]
	s_branch .LBB0_221

; DI float bf2f(bf16_t v) { return __uint_as_float(((unsigned)v) << 16); }
; DI void load_q_norm(bf16x8 (&qf)[8], const bf16_t* qrow, int g, const float* __restrict__ gain, float scale) {
;   float ss = 0.f;
; #pragma unroll
;   for (int ks = 0; ks < 8; ++ks) { qf[ks] = *(const bf16x8*)(qrow + ks * 16 + g * 8);
; #pragma unroll
;     for (int e = 0; e < 8; ++e) { const float f = bf2f((bf16_t)qf[ks][e]); ss += f * f; } }
; DI void nsa_cmp2(const Params& p, const NsaCtx c) {
;     ...
;       for (int jj = 0; jj < 4; ++jj) {
;         const int hh = c.gk * 4 + jj;
;         bf16x8 q2[8];
;         load_q_norm(q2, NQ + ((size_t)(c.b * 16 + hh) * T_ + tq) * 128, g, qgain, ATTN_SCALE * LOG2E);
.LBB0_221:
	global_load_dwordx4 v[150:153], v[140:141], off offset:-128
	global_load_dwordx4 v[114:117], v[140:141], off offset:-96
	global_load_dwordx4 v[110:113], v[140:141], off offset:-64
	global_load_dwordx4 v[154:157], v[140:141], off offset:-32
	global_load_dwordx4 v[106:109], v[140:141], off
	global_load_dwordx4 v[162:165], v[140:141], off offset:32
	global_load_dwordx4 v[166:169], v[140:141], off offset:64
	global_load_dwordx4 v[176:179], v[140:141], off offset:96
	s_add_i32 s9, s5, s8
	s_waitcnt vmcnt(7)
	v_and_b32_e32 v7, 0xffff0000, v150
	v_lshlrev_b32_e32 v6, 16, v150
	v_mul_f32_e32 v0, v7, v7
	v_pk_fma_f32 v[10:11], v[6:7], v[6:7], v[0:1] op_sel_hi:[1,1,0]
	v_and_b32_e32 v9, 0xffff0000, v151
	v_lshlrev_b32_e32 v8, 16, v151
	v_pk_fma_f32 v[2:3], v[8:9], v[8:9], v[10:11]
	v_mul_f32_e32 v0, v9, v9
	v_pk_add_f32 v[2:3], v[0:1], v[2:3] op_sel_hi:[0,1]
	v_and_b32_e32 v11, 0xffff0000, v152
	v_lshlrev_b32_e32 v10, 16, v152
	v_pk_fma_f32 v[2:3], v[10:11], v[10:11], v[2:3]
	v_mul_f32_e32 v0, v11, v11
	v_pk_add_f32 v[2:3], v[0:1], v[2:3] op_sel_hi:[0,1]
	v_and_b32_e32 v13, 0xffff0000, v153
	v_lshlrev_b32_e32 v12, 16, v153
	v_pk_fma_f32 v[2:3], v[12:13], v[12:13], v[2:3]
	v_mul_f32_e32 v0, v13, v13
	v_pk_add_f32 v[16:17], v[0:1], v[2:3] op_sel_hi:[0,1]
	s_waitcnt vmcnt(6)
	v_and_b32_e32 v15, 0xffff0000, v114
	v_lshlrev_b32_e32 v14, 16, v114
	v_pk_fma_f32 v[16:17], v[14:15], v[14:15], v[16:17]
	v_mul_f32_e32 v0, v15, v15
	v_pk_add_f32 v[98:99], v[0:1], v[16:17] op_sel_hi:[0,1]
	v_and_b32_e32 v17, 0xffff0000, v115
	v_lshlrev_b32_e32 v16, 16, v115
	v_pk_fma_f32 v[2:3], v[16:17], v[16:17], v[98:99]
	v_mul_f32_e32 v0, v17, v17
	v_pk_add_f32 v[2:3], v[0:1], v[2:3] op_sel_hi:[0,1]
	v_and_b32_e32 v147, 0xffff0000, v116
	v_lshlrev_b32_e32 v146, 16, v116
	v_pk_fma_f32 v[2:3], v[146:147], v[146:147], v[2:3]
	v_mul_f32_e32 v0, v147, v147
	v_pk_add_f32 v[2:3], v[0:1], v[2:3] op_sel_hi:[0,1]
	v_and_b32_e32 v123, 0xffff0000, v117
	v_lshlrev_b32_e32 v122, 16, v117
	v_pk_fma_f32 v[2:3], v[122:123], v[122:123], v[2:3]
	v_mul_f32_e32 v0, v123, v123
	v_pk_add_f32 v[98:99], v[0:1], v[2:3] op_sel_hi:[0,1]
	s_waitcnt vmcnt(5)
	v_and_b32_e32 v119, 0xffff0000, v110
	v_lshlrev_b32_e32 v118, 16, v110
	v_pk_fma_f32 v[98:99], v[118:119], v[118:119], v[98:99]
	v_mul_f32_e32 v0, v119, v119
	v_pk_add_f32 v[98:99], v[0:1], v[98:99] op_sel_hi:[0,1]
	v_and_b32_e32 v125, 0xffff0000, v111
	v_lshlrev_b32_e32 v124, 16, v111
	v_pk_fma_f32 v[2:3], v[124:125], v[124:125], v[98:99]
	v_mul_f32_e32 v0, v125, v125
	v_pk_add_f32 v[2:3], v[0:1], v[2:3] op_sel_hi:[0,1]
	v_and_b32_e32 v149, 0xffff0000, v112
	v_lshlrev_b32_e32 v148, 16, v112
	v_pk_fma_f32 v[2:3], v[148:149], v[148:149], v[2:3]
	v_mul_f32_e32 v0, v149, v149
	v_pk_add_f32 v[2:3], v[0:1], v[2:3] op_sel_hi:[0,1]
	v_and_b32_e32 v121, 0xffff0000, v113
	v_lshlrev_b32_e32 v120, 16, v113
	v_pk_fma_f32 v[2:3], v[120:121], v[120:121], v[2:3]
	v_mul_f32_e32 v0, v121, v121
	v_pk_add_f32 v[98:99], v[0:1], v[2:3] op_sel_hi:[0,1]
	s_waitcnt vmcnt(4)
	v_and_b32_e32 v115, 0xffff0000, v154
	v_lshlrev_b32_e32 v114, 16, v154
	v_pk_fma_f32 v[98:99], v[114:115], v[114:115], v[98:99]
	v_mul_f32_e32 v0, v115, v115
	v_pk_add_f32 v[98:99], v[0:1], v[98:99] op_sel_hi:[0,1]
	v_and_b32_e32 v151, 0xffff0000, v155
	v_lshlrev_b32_e32 v150, 16, v155
	v_pk_fma_f32 v[2:3], v[150:151], v[150:151], v[98:99]
	v_mul_f32_e32 v0, v151, v151
	v_pk_add_f32 v[2:3], v[0:1], v[2:3] op_sel_hi:[0,1]
	v_and_b32_e32 v153, 0xffff0000, v156
	v_lshlrev_b32_e32 v152, 16, v156
	v_pk_fma_f32 v[2:3], v[152:153], v[152:153], v[2:3]
	v_mul_f32_e32 v0, v153, v153
	v_pk_add_f32 v[2:3], v[0:1], v[2:3] op_sel_hi:[0,1]
	v_and_b32_e32 v117, 0xffff0000, v157
	v_lshlrev_b32_e32 v116, 16, v157
	v_pk_fma_f32 v[2:3], v[116:117], v[116:117], v[2:3]
	v_mul_f32_e32 v0, v117, v117
	v_pk_add_f32 v[98:99], v[0:1], v[2:3] op_sel_hi:[0,1]
	s_waitcnt vmcnt(3)
	v_and_b32_e32 v111, 0xffff0000, v106
	v_lshlrev_b32_e32 v110, 16, v106
	v_pk_fma_f32 v[98:99], v[110:111], v[110:111], v[98:99]
	v_mul_f32_e32 v0, v111, v111
	v_pk_add_f32 v[98:99], v[0:1], v[98:99] op_sel_hi:[0,1]
	v_and_b32_e32 v155, 0xffff0000, v107
	v_lshlrev_b32_e32 v154, 16, v107
	v_pk_fma_f32 v[2:3], v[154:155], v[154:155], v[98:99]
	v_mul_f32_e32 v0, v155, v155
	v_pk_add_f32 v[2:3], v[0:1], v[2:3] op_sel_hi:[0,1]
	v_and_b32_e32 v157, 0xffff0000, v108
	v_lshlrev_b32_e32 v156, 16, v108
	v_pk_fma_f32 v[2:3], v[156:157], v[156:157], v[2:3]
	v_mul_f32_e32 v0, v157, v157
	v_pk_add_f32 v[2:3], v[0:1], v[2:3] op_sel_hi:[0,1]
	v_and_b32_e32 v113, 0xffff0000, v109
	v_lshlrev_b32_e32 v112, 16, v109
	v_pk_fma_f32 v[2:3], v[112:113], v[112:113], v[2:3]
	v_mul_f32_e32 v0, v113, v113
	v_pk_add_f32 v[98:99], v[0:1], v[2:3] op_sel_hi:[0,1]
	s_waitcnt vmcnt(2)
	v_and_b32_e32 v107, 0xffff0000, v162
	v_lshlrev_b32_e32 v106, 16, v162
	v_pk_fma_f32 v[98:99], v[106:107], v[106:107], v[98:99]
	v_mul_f32_e32 v0, v107, v107
	v_pk_add_f32 v[98:99], v[0:1], v[98:99] op_sel_hi:[0,1]
	v_and_b32_e32 v159, 0xffff0000, v163
	v_lshlrev_b32_e32 v158, 16, v163
	v_pk_fma_f32 v[2:3], v[158:159], v[158:159], v[98:99]
	v_mul_f32_e32 v0, v159, v159
	v_pk_add_f32 v[2:3], v[0:1], v[2:3] op_sel_hi:[0,1]
	v_and_b32_e32 v161, 0xffff0000, v164
	v_lshlrev_b32_e32 v160, 16, v164
	v_pk_fma_f32 v[2:3], v[160:161], v[160:161], v[2:3]
	v_mul_f32_e32 v0, v161, v161
	v_pk_add_f32 v[2:3], v[0:1], v[2:3] op_sel_hi:[0,1]
	v_and_b32_e32 v109, 0xffff0000, v165
	v_lshlrev_b32_e32 v108, 16, v165
	v_pk_fma_f32 v[2:3], v[108:109], v[108:109], v[2:3]
	v_mul_f32_e32 v0, v109, v109
	v_pk_add_f32 v[98:99], v[0:1], v[2:3] op_sel_hi:[0,1]
	s_waitcnt vmcnt(1)
; DI float bf2f(bf16_t v) { return __uint_as_float(((unsigned)v) << 16); }
; DI unsigned pk2(float lo, float hi) { const f32x2g f = {lo, hi}; const hwbf16x2g r = __builtin_convertvector(f, hwbf16x2g); return __builtin_bit_cast(unsigned, r); }
; DI float xhalf_sum(float v) { const auto r = __builtin_amdgcn_permlane32_swap(__float_as_uint(v), __float_as_uint(v), false, false); return __uint_as_float(r[0]) + __uint_as_float(r[1]); }
; DI float fexp2(float x) { return __builtin_amdgcn_exp2f(x); }
; DI void load_q_norm(bf16x8 (&qf)[8], const bf16_t* qrow, int g, const float* __restrict__ gain, float scale) {
;     ...
;     for (int e = 0; e < 8; ++e) { const float f = bf2f((bf16_t)qf[ks][e]); ss += f * f; } }
;   ss = xhalf_sum(ss);
;   const float rs = rsqrtf(ss * (1.f / 128.f) + EPS_) * scale;
; #pragma unroll
;   for (int ks = 0; ks < 8; ++ks) {
;     const f32x4 g0 = *(const f32x4*)(gain + ks * 16 + g * 8), g1 = *(const f32x4*)(gain + ks * 16 + g * 8 + 4);
;     u32x4 o;
;     o.x = pk2(bf2f((bf16_t)qf[ks][0]) * rs * g0[0], bf2f((bf16_t)qf[ks][1]) * rs * g0[1]);
;     o.y = pk2(bf2f((bf16_t)qf[ks][2]) * rs * g0[2], bf2f((bf16_t)qf[ks][3]) * rs * g0[3]);
;     o.z = pk2(bf2f((bf16_t)qf[ks][4]) * rs * g1[0], bf2f((bf16_t)qf[ks][5]) * rs * g1[1]);
;     o.w = pk2(bf2f((bf16_t)qf[ks][6]) * rs * g1[2], bf2f((bf16_t)qf[ks][7]) * rs * g1[3]);
;     qf[ks] = __builtin_bit_cast(bf16x8, o);
;   }
; DI void nsa_cmp2(const Params& p, const NsaCtx c) {
;     ...
;         const float sl2 = fexp2(-0.5f * (float)(hh + 1)) * LOG2E;
;         if (t0 - (16 * (32 * kt + 31) + 16) > __builtin_amdgcn_readfirstlane((int)(200.f / sl2) + 1) + 32) continue;
	v_and_b32_e32 v103, 0xffff0000, v166
	v_lshlrev_b32_e32 v102, 16, v166
	v_pk_fma_f32 v[98:99], v[102:103], v[102:103], v[98:99]
	v_mul_f32_e32 v0, v103, v103
	v_pk_add_f32 v[98:99], v[0:1], v[98:99] op_sel_hi:[0,1]
	v_and_b32_e32 v163, 0xffff0000, v167
	v_lshlrev_b32_e32 v162, 16, v167
	v_pk_fma_f32 v[2:3], v[162:163], v[162:163], v[98:99]
	v_mul_f32_e32 v0, v163, v163
	v_pk_add_f32 v[2:3], v[0:1], v[2:3] op_sel_hi:[0,1]
	v_and_b32_e32 v165, 0xffff0000, v168
	v_lshlrev_b32_e32 v164, 16, v168
	v_pk_fma_f32 v[2:3], v[164:165], v[164:165], v[2:3]
	v_mul_f32_e32 v0, v165, v165
	v_pk_add_f32 v[2:3], v[0:1], v[2:3] op_sel_hi:[0,1]
	v_and_b32_e32 v105, 0xffff0000, v169
	v_lshlrev_b32_e32 v104, 16, v169
	v_pk_fma_f32 v[2:3], v[104:105], v[104:105], v[2:3]
	v_mul_f32_e32 v0, v105, v105
	v_pk_add_f32 v[98:99], v[0:1], v[2:3] op_sel_hi:[0,1]
	s_waitcnt vmcnt(0)
	v_and_b32_e32 v167, 0xffff0000, v176
	v_lshlrev_b32_e32 v166, 16, v176
	v_pk_fma_f32 v[98:99], v[166:167], v[166:167], v[98:99]
	v_mul_f32_e32 v0, v167, v167
	v_pk_add_f32 v[98:99], v[0:1], v[98:99] op_sel_hi:[0,1]
	v_and_b32_e32 v169, 0xffff0000, v177
	v_lshlrev_b32_e32 v168, 16, v177
	v_pk_fma_f32 v[2:3], v[168:169], v[168:169], v[98:99]
	v_mul_f32_e32 v0, v169, v169
	v_pk_add_f32 v[98:99], v[0:1], v[2:3] op_sel_hi:[0,1]
	v_and_b32_e32 v3, 0xffff0000, v178
	v_lshlrev_b32_e32 v2, 16, v178
	v_pk_fma_f32 v[98:99], v[2:3], v[2:3], v[98:99]
	v_mul_f32_e32 v0, v3, v3
	v_pk_add_f32 v[100:101], v[0:1], v[98:99] op_sel_hi:[0,1]
	v_and_b32_e32 v99, 0xffff0000, v179
	v_lshlrev_b32_e32 v98, 16, v179
	v_pk_fma_f32 v[4:5], v[98:99], v[98:99], v[100:101]
	v_mul_f32_e32 v0, v99, v99
	v_pk_add_f32 v[4:5], v[0:1], v[4:5] op_sel_hi:[0,1]
	v_cvt_f32_u32_e32 v0, s9
	v_mov_b32_e32 v5, v4
	s_nop 1
	v_permlane32_swap_b32_e32 v4, v5
	v_mul_f32_e32 v0, -0.5, v0
	v_exp_f32_e32 v0, v0
	s_nop 0
	v_mul_f32_e32 v0, 0x3fb8aa3b, v0
	s_nop 0
	v_readfirstlane_b32 s9, v0
	s_nop 1
	v_div_scale_f32 v100, s[10:11], s9, s9, v192
	v_rcp_f32_e32 v101, v100
	s_mov_b32 s10, 0x43480000
	v_fma_f32 v176, -v100, v101, 1.0
	v_fmac_f32_e32 v101, v176, v101
	v_mov_b32_e32 v176, s9
	v_div_scale_f32 v176, vcc, s10, v176, s10
	v_mul_f32_e32 v177, v176, v101
	v_fma_f32 v178, -v100, v177, v176
	v_fmac_f32_e32 v177, v178, v101
	v_fma_f32 v100, -v100, v177, v176
	v_div_fmas_f32 v100, v100, v101, v177
	v_div_fixup_f32 v100, v100, s9, v192
	v_cvt_i32_f32_e32 v100, v100
	v_add_u32_e32 v100, 33, v100
	v_cmp_gt_i32_e32 vcc, s7, v100
	s_cbranch_vccnz .LBB0_220
	v_add_f32_e32 v4, v4, v5
	v_fmamk_f32 v4, v4, 0x3c000000, v249
	v_cmp_gt_f32_e32 vcc, s84, v4
	v_mul_f32_e32 v5, 0x4b800000, v4
	s_nop 0
	v_cndmask_b32_e32 v4, v4, v5, vcc
	v_rsq_f32_e32 v4, v4
	s_nop 0
	v_mul_f32_e32 v5, 0x45800000, v4
	v_cndmask_b32_e32 v4, v4, v5, vcc
	v_mul_f32_e32 v4, 0x3e0293ee, v4
	v_pk_mul_f32 v[2:3], v[4:5], v[2:3] op_sel_hi:[0,1]
	v_pk_mul_f32 v[2:3], v[74:75], v[2:3]
	v_pk_mul_f32 v[98:99], v[4:5], v[98:99] op_sel_hi:[0,1]
	v_cvt_pk_bf16_f32 v100, v2, v3
	v_pk_mul_f32 v[2:3], v[4:5], v[104:105] op_sel_hi:[0,1]
	v_pk_mul_f32 v[2:3], v[68:69], v[2:3]
	v_pk_mul_f32 v[98:99], v[76:77], v[98:99]
	v_cvt_pk_bf16_f32 v105, v2, v3
	v_pk_mul_f32 v[2:3], v[4:5], v[102:103] op_sel_hi:[0,1]
	v_pk_mul_f32 v[2:3], v[70:71], v[2:3]
	v_cvt_pk_bf16_f32 v101, v98, v99
	v_cvt_pk_bf16_f32 v102, v2, v3
	v_pk_mul_f32 v[2:3], v[4:5], v[162:163] op_sel_hi:[0,1]
	v_pk_mul_f32 v[2:3], v[72:73], v[2:3]
	v_pk_mul_f32 v[98:99], v[4:5], v[166:167] op_sel_hi:[0,1]
	v_cvt_pk_bf16_f32 v103, v2, v3
	v_pk_mul_f32 v[2:3], v[4:5], v[164:165] op_sel_hi:[0,1]
	v_pk_mul_f32 v[2:3], v[66:67], v[2:3]
	v_pk_mul_f32 v[166:167], v[4:5], v[168:169] op_sel_hi:[0,1]
	v_cvt_pk_bf16_f32 v104, v2, v3
	v_pk_mul_f32 v[2:3], v[4:5], v[108:109] op_sel_hi:[0,1]
	v_pk_mul_f32 v[2:3], v[60:61], v[2:3]
	v_pk_mul_f32 v[98:99], v[78:79], v[98:99]
	v_cvt_pk_bf16_f32 v109, v2, v3
	v_pk_mul_f32 v[2:3], v[4:5], v[106:107] op_sel_hi:[0,1]
	v_pk_mul_f32 v[2:3], v[62:63], v[2:3]
	v_pk_mul_f32 v[166:167], v[80:81], v[166:167]
	v_cvt_pk_bf16_f32 v106, v2, v3
	v_pk_mul_f32 v[2:3], v[4:5], v[158:159] op_sel_hi:[0,1]
	v_pk_mul_f32 v[2:3], v[64:65], v[2:3]
	v_cvt_pk_bf16_f32 v98, v98, v99
	v_cvt_pk_bf16_f32 v107, v2, v3
	v_pk_mul_f32 v[2:3], v[4:5], v[160:161] op_sel_hi:[0,1]
	v_pk_mul_f32 v[2:3], v[58:59], v[2:3]
	v_cvt_pk_bf16_f32 v99, v166, v167
	v_cvt_pk_bf16_f32 v108, v2, v3
	v_pk_mul_f32 v[2:3], v[4:5], v[112:113] op_sel_hi:[0,1]
	v_pk_mul_f32 v[2:3], v[52:53], v[2:3]
	s_nop 0
	v_cvt_pk_bf16_f32 v113, v2, v3
	v_pk_mul_f32 v[2:3], v[4:5], v[110:111] op_sel_hi:[0,1]
	v_pk_mul_f32 v[2:3], v[54:55], v[2:3]
	s_nop 0
	v_cvt_pk_bf16_f32 v110, v2, v3
	v_pk_mul_f32 v[2:3], v[4:5], v[154:155] op_sel_hi:[0,1]
	v_pk_mul_f32 v[2:3], v[56:57], v[2:3]
	s_nop 0
	v_cvt_pk_bf16_f32 v111, v2, v3
	v_pk_mul_f32 v[2:3], v[4:5], v[156:157] op_sel_hi:[0,1]
	v_pk_mul_f32 v[2:3], v[50:51], v[2:3]
	s_nop 0
	v_cvt_pk_bf16_f32 v112, v2, v3
	v_pk_mul_f32 v[2:3], v[4:5], v[116:117] op_sel_hi:[0,1]
	v_pk_mul_f32 v[2:3], v[44:45], v[2:3]
	s_nop 0
	v_cvt_pk_bf16_f32 v117, v2, v3
	v_pk_mul_f32 v[2:3], v[4:5], v[114:115] op_sel_hi:[0,1]
	v_pk_mul_f32 v[2:3], v[46:47], v[2:3]
	s_nop 0
	v_cvt_pk_bf16_f32 v114, v2, v3
	v_pk_mul_f32 v[2:3], v[4:5], v[150:151] op_sel_hi:[0,1]
	v_pk_mul_f32 v[2:3], v[48:49], v[2:3]
; DI float bf2f(bf16_t v) { return __uint_as_float(((unsigned)v) << 16); }
; DI unsigned pk2(float lo, float hi) { const f32x2g f = {lo, hi}; const hwbf16x2g r = __builtin_convertvector(f, hwbf16x2g); return __builtin_bit_cast(unsigned, r); }
; DI float fexp2(float x) { return __builtin_amdgcn_exp2f(x); }
; DI int crow(int i, int g) { return (i & 3) + 8 * (i >> 2) + 4 * g; }
; DI void load_q_norm(bf16x8 (&qf)[8], const bf16_t* qrow, int g, const float* __restrict__ gain, float scale) {
;     ...
;   for (int ks = 0; ks < 8; ++ks) {
;     const f32x4 g0 = *(const f32x4*)(gain + ks * 16 + g * 8), g1 = *(const f32x4*)(gain + ks * 16 + g * 8 + 4);
;     u32x4 o;
;     o.x = pk2(bf2f((bf16_t)qf[ks][0]) * rs * g0[0], bf2f((bf16_t)qf[ks][1]) * rs * g0[1]);
;     o.y = pk2(bf2f((bf16_t)qf[ks][2]) * rs * g0[2], bf2f((bf16_t)qf[ks][3]) * rs * g0[3]);
;     o.z = pk2(bf2f((bf16_t)qf[ks][4]) * rs * g1[0], bf2f((bf16_t)qf[ks][5]) * rs * g1[1]);
;     o.w = pk2(bf2f((bf16_t)qf[ks][6]) * rs * g1[2], bf2f((bf16_t)qf[ks][7]) * rs * g1[3]);
;     qf[ks] = __builtin_bit_cast(bf16x8, o);
;   }
; DI void nsa_cmp2(const Params& p, const NsaCtx c) {
;     ...
;         if (t0 - (16 * (32 * kt + 31) + 16) > __builtin_amdgcn_readfirstlane((int)(200.f / sl2) + 1) + 32) continue;
;         const float mm = ml[((sub * 4 + jj) * 32 + lr) * 2], iv = ml[((sub * 4 + jj) * 32 + lr) * 2 + 1];
;         f32x16 acc = score_tile(q2, KCMP + (size_t)kt * 32 * 128, koff);
; #pragma unroll
;         for (int i = 0; i < 16; ++i) {
;           const int n = kt * 32 + crow(i, g);
;           const float s = acc[i] - sl2 * (ftq - ((float)(16 * n) + 15.5f));
;           const float pr = (16 * n + 31 <= tq) ? fexp2(s - mm) * iv : 0.f;
;           ps[i] += pr;
;         }
	s_nop 0
	v_cvt_pk_bf16_f32 v115, v2, v3
	v_pk_mul_f32 v[2:3], v[4:5], v[152:153] op_sel_hi:[0,1]
	v_pk_mul_f32 v[2:3], v[42:43], v[2:3]
	s_nop 0
	v_cvt_pk_bf16_f32 v116, v2, v3
	v_pk_mul_f32 v[2:3], v[4:5], v[120:121] op_sel_hi:[0,1]
	v_pk_mul_f32 v[2:3], v[36:37], v[2:3]
	s_nop 0
	v_cvt_pk_bf16_f32 v121, v2, v3
	v_pk_mul_f32 v[2:3], v[4:5], v[118:119] op_sel_hi:[0,1]
	v_pk_mul_f32 v[2:3], v[38:39], v[2:3]
	s_nop 0
	v_cvt_pk_bf16_f32 v118, v2, v3
	v_pk_mul_f32 v[2:3], v[4:5], v[124:125] op_sel_hi:[0,1]
	v_pk_mul_f32 v[2:3], v[40:41], v[2:3]
	s_nop 0
	v_cvt_pk_bf16_f32 v119, v2, v3
	v_pk_mul_f32 v[2:3], v[4:5], v[148:149] op_sel_hi:[0,1]
	v_pk_mul_f32 v[2:3], v[34:35], v[2:3]
	v_cvt_pk_bf16_f32 v120, v2, v3
	v_pk_mul_f32 v[2:3], v[4:5], v[122:123] op_sel_hi:[0,1]
	v_pk_mul_f32 v[2:3], v[28:29], v[2:3]
	s_nop 0
	v_cvt_pk_bf16_f32 v125, v2, v3
	v_pk_mul_f32 v[2:3], v[4:5], v[14:15] op_sel_hi:[0,1]
	v_pk_mul_f32 v[2:3], v[30:31], v[2:3]
	s_nop 0
	v_cvt_pk_bf16_f32 v122, v2, v3
	v_pk_mul_f32 v[2:3], v[4:5], v[16:17] op_sel_hi:[0,1]
	v_pk_mul_f32 v[2:3], v[32:33], v[2:3]
	s_nop 0
	v_cvt_pk_bf16_f32 v123, v2, v3
	v_pk_mul_f32 v[2:3], v[4:5], v[146:147] op_sel_hi:[0,1]
	v_pk_mul_f32 v[2:3], v[26:27], v[2:3]
	s_nop 0
	v_cvt_pk_bf16_f32 v124, v2, v3
	v_pk_mul_f32 v[2:3], v[4:5], v[12:13] op_sel_hi:[0,1]
	v_pk_mul_f32 v[2:3], v[20:21], v[2:3]
	s_nop 0
	v_cvt_pk_bf16_f32 v5, v2, v3
	v_pk_mul_f32 v[2:3], v[4:5], v[6:7] op_sel_hi:[0,1]
	v_pk_mul_f32 v[6:7], v[4:5], v[8:9] op_sel_hi:[0,1]
	v_pk_mul_f32 v[2:3], v[22:23], v[2:3]
	v_pk_mul_f32 v[6:7], v[24:25], v[6:7]
	v_cvt_pk_bf16_f32 v2, v2, v3
	v_cvt_pk_bf16_f32 v3, v6, v7
	v_pk_mul_f32 v[6:7], v[4:5], v[10:11] op_sel_hi:[0,1]
	v_pk_mul_f32 v[6:7], v[18:19], v[6:7]
	s_nop 0
	v_cvt_pk_bf16_f32 v4, v6, v7
	v_add_u32_e32 v6, -4, v207
	ds_read_b64 v[146:147], v6
	s_waitcnt vmcnt(0)
	v_mfma_f32_32x32x16_bf16 v[2:17], v[186:189], v[2:5], 0
	v_mfma_f32_32x32x16_bf16 v[2:17], v[194:197], v[122:125], v[2:17]
	v_mfma_f32_32x32x16_bf16 v[2:17], v[200:203], v[118:121], v[2:17]
	v_mfma_f32_32x32x16_bf16 v[2:17], v[228:231], v[114:117], v[2:17]
	v_mfma_f32_32x32x16_bf16 v[2:17], v[232:235], v[110:113], v[2:17]
	v_mfma_f32_32x32x16_bf16 v[2:17], v[236:239], v[106:109], v[2:17]
	v_mfma_f32_32x32x16_bf16 v[2:17], v[240:243], v[102:105], v[2:17]
	v_mfma_f32_32x32x16_bf16 v[2:17], v[244:247], v[98:101], v[2:17]
	s_nop 11
	v_fma_f32 v2, -v83, v0, v2
	s_waitcnt lgkmcnt(0)
	v_sub_f32_e32 v2, v2, v146
	v_exp_f32_e32 v2, v2
	s_nop 0
	v_mul_f32_e32 v2, v147, v2
	v_cndmask_b32_e64 v2, v2, 0, s[38:39]
	v_add_f32_e32 v94, v94, v2
	v_fma_f32 v2, -v84, v0, v3
	v_fma_f32 v3, -v87, v0, v4
	v_sub_f32_e32 v2, v2, v146
	v_sub_f32_e32 v3, v3, v146
	v_exp_f32_e32 v2, v2
	v_exp_f32_e32 v3, v3
	s_nop 0
	v_pk_mul_f32 v[2:3], v[146:147], v[2:3] op_sel:[1,0]
	s_nop 0
	v_cndmask_b32_e64 v3, v3, 0, s[40:41]
	v_cndmask_b32_e64 v2, v2, 0, s[42:43]
	v_pk_add_f32 v[144:145], v[144:145], v[2:3]
	v_fma_f32 v2, -v88, v0, v5
	v_sub_f32_e32 v2, v2, v146
	v_exp_f32_e32 v2, v2
	v_fma_f32 v3, -v95, v0, v8
	v_sub_f32_e32 v3, v3, v146
	v_exp_f32_e32 v3, v3
	v_mul_f32_e32 v2, v147, v2
	v_cndmask_b32_e64 v2, v2, 0, s[44:45]
	v_add_f32_e32 v97, v97, v2
	v_fma_f32 v2, -v91, v0, v6
	v_sub_f32_e32 v2, v2, v146
	v_exp_f32_e32 v2, v2
	s_nop 0
	v_mul_f32_e32 v2, v147, v2
	v_cndmask_b32_e64 v2, v2, 0, s[46:47]
	v_add_f32_e32 v90, v90, v2
	v_fma_f32 v2, -v92, v0, v7
	v_sub_f32_e32 v2, v2, v146
	v_exp_f32_e32 v2, v2
	s_nop 0
	v_pk_mul_f32 v[2:3], v[146:147], v[2:3] op_sel:[1,0]
	s_nop 0
	v_cndmask_b32_e64 v3, v3, 0, s[48:49]
	v_cndmask_b32_e64 v2, v2, 0, s[50:51]
	v_pk_add_f32 v[142:143], v[142:143], v[2:3]
	v_fma_f32 v2, -v96, v0, v9
	v_sub_f32_e32 v2, v2, v146
	v_exp_f32_e32 v2, v2
	v_fma_f32 v3, -v180, v0, v12
	v_sub_f32_e32 v3, v3, v146
	v_exp_f32_e32 v3, v3
	v_mul_f32_e32 v2, v147, v2
	v_cndmask_b32_e64 v2, v2, 0, s[52:53]
	v_add_f32_e32 v93, v93, v2
	v_fma_f32 v2, -v174, v0, v10
	v_sub_f32_e32 v2, v2, v146
	v_exp_f32_e32 v2, v2
	s_nop 0
	v_mul_f32_e32 v2, v147, v2
	v_cndmask_b32_e64 v2, v2, 0, s[54:55]
	v_add_f32_e32 v86, v86, v2
	v_fma_f32 v2, -v175, v0, v11
	v_sub_f32_e32 v2, v2, v146
	v_exp_f32_e32 v2, v2
	s_nop 0
	v_pk_mul_f32 v[2:3], v[146:147], v[2:3] op_sel:[1,0]
	s_nop 0
	v_cndmask_b32_e64 v3, v3, 0, s[56:57]
	v_cndmask_b32_e64 v2, v2, 0, s[58:59]
	v_pk_add_f32 v[138:139], v[138:139], v[2:3]
	v_fma_f32 v2, -v181, v0, v13
	v_sub_f32_e32 v2, v2, v146
	v_exp_f32_e32 v2, v2
	v_fma_f32 v3, -v184, v0, v16
	v_sub_f32_e32 v3, v3, v146
	v_exp_f32_e32 v3, v3
	v_mul_f32_e32 v2, v147, v2
	v_cndmask_b32_e64 v2, v2, 0, s[60:61]
	v_add_f32_e32 v89, v89, v2
	v_fma_f32 v2, -v182, v0, v14
	v_sub_f32_e32 v2, v2, v146
	v_exp_f32_e32 v2, v2
	s_nop 0
	v_mul_f32_e32 v2, v147, v2
	v_cndmask_b32_e64 v2, v2, 0, s[62:63]
	v_add_f32_e32 v82, v82, v2
	v_fma_f32 v2, -v183, v0, v15
	v_fma_f32 v0, -v185, v0, v17
	v_sub_f32_e32 v2, v2, v146
	v_sub_f32_e32 v0, v0, v146
	v_exp_f32_e32 v2, v2
	v_exp_f32_e32 v0, v0
	v_pk_mul_f32 v[2:3], v[146:147], v[2:3] op_sel:[1,0]
	v_mul_f32_e32 v0, v147, v0
	v_cndmask_b32_e64 v3, v3, 0, s[64:65]
	v_cndmask_b32_e64 v2, v2, 0, s[66:67]
	v_cndmask_b32_e64 v0, v0, 0, s[68:69]
	v_pk_add_f32 v[136:137], v[136:137], v[2:3]
	v_add_f32_e32 v85, v85, v0
	s_branch .LBB0_220
